# D2: qg section issues all 32 row loads up front with counted waits (was 16 serial load-wait-store round trips); on top of DPP forward substitution
# baseline (speedup 1.0000x reference)
; #define MFMA32(a, b, c) __builtin_amdgcn_mfma_f32_32x32x16_bf16((a), (b), (c), 0, 0, 0)
; DI unsigned cvtpk(float lo, float hi) { f32x2 v = {lo, hi}; bf16x2_t b = __builtin_convertvector(v, bf16x2_t); return __builtin_bit_cast(unsigned, b); }
; DI float bflo(unsigned u) { return __uint_as_float(u << 16); }
; DI float bfhi(unsigned u) { return __uint_as_float(u & 0xffff0000u); }
; DI void d2_chunk(const Params& P, int l, int chunk, LAS float* Nm, LAS float* gs, int lane_in) {
;     ...
;         for (int dt = 0; dt < 4; ++dt) {
;             f32x16 u0, u1;
; #pragma unroll
;             for (int i = 0; i < 16; ++i) { u0[i] = 0.f; u1[i] = 0.f; }
; #pragma unroll
;             for (int ks = 0; ks < 4; ++ks) { const bf16x8 vfr = D2_XFRAG(dt, ks); u0 = MFMA32(Tfu[0][ks], vfr, u0); u1 = MFMA32(Tfu[1][ks], vfr, u1); }
;             *(bf16x8*)(UF + ((dt * 2 + 0) * 64 + lane) * 16) = pack8(u0, 0); *(bf16x8*)(UF + ((dt * 2 + 0) * 64 + lane) * 16 + 8) = pack8(u0, 1);
;             *(bf16x8*)(UF + ((dt * 2 + 1) * 64 + lane) * 16) = pack8(u1, 0); *(bf16x8*)(UF + ((dt * 2 + 1) * 64 + lane) * 16 + 8) = pack8(u1, 1);
;         }
;     ...
;     for (int t = 0; t < 2; ++t) { const float f = __expf(gs[32 * t + r]); const bf16_t* qrow = Qc + (32 * t + r) * 128 + 4 * hi;
; #pragma unroll
;         for (int G = 0; G < 8; ++G) { const u32x2 a = *(const u32x2*)(qrow + 16 * G), c2 = *(const u32x2*)(qrow + 16 * G + 8);
;             u32x4 o; o.x = cvtpk(bflo(a.x) * f, bfhi(a.x) * f); o.y = cvtpk(bflo(a.y) * f, bfhi(a.y) * f); o.z = cvtpk(bflo(c2.x) * f, bfhi(c2.x) * f); o.w = cvtpk(bflo(c2.y) * f, bfhi(c2.y) * f);
;             *(u32x4*)(QGf + ((t * 8 + G) * 64 + lane) * 8) = o; } }
.LBB0_484:
	v_add_u32_e32 v68, s8, v167
	ds_read_u16 v0, v68
	ds_read_u16 v1, v68 offset:256
	v_ashrrev_i32_e32 v179, 31, v178
	s_add_i32 s8, s8, 64
	s_cmpk_lg_i32 s8, 0x100
	s_waitcnt lgkmcnt(0)
	v_lshl_or_b32 v0, v1, 16, v0
	ds_read_u16 v1, v68 offset:512
	ds_read_u16 v2, v68 offset:768
	s_waitcnt lgkmcnt(0)
	v_lshl_or_b32 v1, v2, 16, v1
	ds_read_u16 v2, v68 offset:1024
	ds_read_u16 v3, v68 offset:1280
	s_waitcnt lgkmcnt(0)
	v_lshl_or_b32 v2, v3, 16, v2
	ds_read_u16 v3, v68 offset:1536
	ds_read_u16 v4, v68 offset:1792
	ds_read_u16 v64, v68 offset:4096
	ds_read_u16 v65, v68 offset:4352
	s_waitcnt lgkmcnt(2)
	v_lshl_or_b32 v3, v4, 16, v3
	s_waitcnt lgkmcnt(0)
	v_lshl_or_b32 v64, v65, 16, v64
	ds_read_u16 v65, v68 offset:4608
	ds_read_u16 v66, v68 offset:4864
	v_mfma_f32_32x32x16_bf16 v[16:31], v[32:35], v[0:3], 0
	s_waitcnt lgkmcnt(0)
	v_lshl_or_b32 v65, v66, 16, v65
	ds_read_u16 v66, v68 offset:5120
	ds_read_u16 v67, v68 offset:5376
	s_waitcnt lgkmcnt(0)
	v_lshl_or_b32 v66, v67, 16, v66
	v_mfma_f32_32x32x16_bf16 v[0:15], v[48:51], v[0:3], 0
	ds_read_u16 v67, v68 offset:5632
	ds_read_u16 v69, v68 offset:5888
	s_waitcnt lgkmcnt(0)
	v_lshl_or_b32 v67, v69, 16, v67
	s_nop 1
	v_mfma_f32_32x32x16_bf16 v[16:31], v[36:39], v[64:67], v[16:31]
	v_mfma_f32_32x32x16_bf16 v[0:15], v[52:55], v[64:67], v[0:15]
	ds_read_u16 v64, v68 offset:8192
	ds_read_u16 v65, v68 offset:8448
	s_waitcnt lgkmcnt(0)
	v_lshl_or_b32 v64, v65, 16, v64
	ds_read_u16 v65, v68 offset:8704
	ds_read_u16 v66, v68 offset:8960
	s_waitcnt lgkmcnt(0)
	v_lshl_or_b32 v65, v66, 16, v65
	ds_read_u16 v66, v68 offset:9216
	ds_read_u16 v67, v68 offset:9472
	s_waitcnt lgkmcnt(0)
	v_lshl_or_b32 v66, v67, 16, v66
	ds_read_u16 v67, v68 offset:9728
	ds_read_u16 v69, v68 offset:9984
	s_waitcnt lgkmcnt(0)
	v_lshl_or_b32 v67, v69, 16, v67
	s_nop 1
	v_mfma_f32_32x32x16_bf16 v[16:31], v[40:43], v[64:67], v[16:31]
	v_mfma_f32_32x32x16_bf16 v[0:15], v[56:59], v[64:67], v[0:15]
	ds_read_u16 v64, v68 offset:12288
	ds_read_u16 v65, v68 offset:12544
	s_waitcnt lgkmcnt(0)
	v_lshl_or_b32 v64, v65, 16, v64
	ds_read_u16 v65, v68 offset:12800
	ds_read_u16 v66, v68 offset:13056
	s_waitcnt lgkmcnt(0)
	v_lshl_or_b32 v65, v66, 16, v65
	ds_read_u16 v66, v68 offset:13312
	ds_read_u16 v67, v68 offset:13568
	s_waitcnt lgkmcnt(0)
	v_lshl_or_b32 v66, v67, 16, v66
	ds_read_u16 v67, v68 offset:13824
	ds_read_u16 v68, v68 offset:14080
	s_waitcnt lgkmcnt(0)
	v_lshl_or_b32 v67, v68, 16, v67
	s_nop 1
	v_mfma_f32_32x32x16_bf16 v[0:15], v[60:63], v[64:67], v[0:15]
	v_mfma_f32_32x32x16_bf16 v[16:31], v[44:47], v[64:67], v[16:31]
	s_nop 10
	v_cvt_pk_bf16_f32 v0, v0, v1
	v_cvt_pk_bf16_f32 v1, v2, v3
	v_cvt_pk_bf16_f32 v2, v4, v5
	v_add_u32_e32 v4, 0x400, v178
	v_ashrrev_i32_e32 v5, 31, v4
	v_cvt_pk_bf16_f32 v3, v6, v7
	v_lshl_add_u64 v[4:5], v[4:5], 1, s[0:1]
	v_cvt_pk_bf16_f32 v16, v16, v17
	v_cvt_pk_bf16_f32 v17, v18, v19
	v_cvt_pk_bf16_f32 v18, v20, v21
	v_cvt_pk_bf16_f32 v19, v22, v23
	v_lshl_add_u64 v[20:21], v[178:179], 1, s[0:1]
	global_store_dwordx4 v[20:21], v[16:19], off
	global_store_dwordx4 v[4:5], v[0:3], off
	v_add_u32_e32 v178, 0x800, v178
	v_cvt_pk_bf16_f32 v16, v24, v25
	v_cvt_pk_bf16_f32 v17, v26, v27
	v_cvt_pk_bf16_f32 v18, v28, v29
	v_cvt_pk_bf16_f32 v19, v30, v31
	v_cvt_pk_bf16_f32 v0, v8, v9
	v_cvt_pk_bf16_f32 v1, v10, v11
	v_cvt_pk_bf16_f32 v2, v12, v13
	v_cvt_pk_bf16_f32 v3, v14, v15
	global_store_dwordx4 v[20:21], v[16:19], off offset:16
	global_store_dwordx4 v[4:5], v[0:3], off offset:16
	s_cbranch_scc1 .LBB0_484
	v_readlane_b32 s0, v254, 58
	v_readlane_b32 s1, v254, 59
	s_add_u32 s4, s0, s4
	s_addc_u32 s5, s1, s5
	v_readlane_b32 s0, v255, 17
	s_add_u32 s0, s0, s38
	v_readlane_b32 s1, v255, 18
	s_addc_u32 s1, s1, s39
	v_ashrrev_i32_e32 v169, 31, v168
	v_lshl_add_u64 v[2:3], v[168:169], 1, s[4:5]
	v_lshlrev_b32_e32 v96, 8, v96
	v_lshl_add_u64 v[6:7], v[2:3], 0, v[96:97]
	ds_read2_b32 v[0:1], v243 offset1:32
	v_lshlrev_b32_e32 v96, 8, v242
	v_lshl_add_u64 v[2:3], v[2:3], 0, v[96:97]
	global_load_dwordx2 v[20:21], v[6:7], off
	global_load_dwordx2 v[22:23], v[6:7], off offset:16
	global_load_dwordx2 v[24:25], v[6:7], off offset:32
	global_load_dwordx2 v[26:27], v[6:7], off offset:48
	global_load_dwordx2 v[28:29], v[6:7], off offset:64
	global_load_dwordx2 v[30:31], v[6:7], off offset:80
	global_load_dwordx2 v[32:33], v[6:7], off offset:96
	global_load_dwordx2 v[34:35], v[6:7], off offset:112
	global_load_dwordx2 v[36:37], v[6:7], off offset:128
	global_load_dwordx2 v[38:39], v[6:7], off offset:144
	global_load_dwordx2 v[40:41], v[6:7], off offset:160
	global_load_dwordx2 v[42:43], v[6:7], off offset:176
	global_load_dwordx2 v[44:45], v[6:7], off offset:192
	global_load_dwordx2 v[46:47], v[6:7], off offset:208
	global_load_dwordx2 v[48:49], v[6:7], off offset:224
	global_load_dwordx2 v[50:51], v[6:7], off offset:240
	global_load_dwordx2 v[52:53], v[2:3], off
	global_load_dwordx2 v[54:55], v[2:3], off offset:16
	global_load_dwordx2 v[56:57], v[2:3], off offset:32
	global_load_dwordx2 v[58:59], v[2:3], off offset:48
	global_load_dwordx2 v[60:61], v[2:3], off offset:64
	global_load_dwordx2 v[62:63], v[2:3], off offset:80
	global_load_dwordx2 v[64:65], v[2:3], off offset:96
	global_load_dwordx2 v[66:67], v[2:3], off offset:112
	global_load_dwordx2 v[68:69], v[2:3], off offset:128
	global_load_dwordx2 v[70:71], v[2:3], off offset:144
	global_load_dwordx2 v[72:73], v[2:3], off offset:160
	global_load_dwordx2 v[74:75], v[2:3], off offset:176
	global_load_dwordx2 v[76:77], v[2:3], off offset:192
	global_load_dwordx2 v[78:79], v[2:3], off offset:208
	global_load_dwordx2 v[80:81], v[2:3], off offset:224
	global_load_dwordx2 v[82:83], v[2:3], off offset:240
	v_lshl_add_u64 v[8:9], v[94:95], 1, s[0:1]
	v_add_u32_e32 v10, 0x800, v94
	v_ashrrev_i32_e32 v11, 31, v10
	v_lshl_add_u64 v[10:11], v[10:11], 1, s[0:1]
	v_add_u32_e32 v12, 0x1000, v94
	v_ashrrev_i32_e32 v13, 31, v12
	v_lshl_add_u64 v[12:13], v[12:13], 1, s[0:1]
	v_add_u32_e32 v14, 0x1800, v94
	v_ashrrev_i32_e32 v15, 31, v14
	v_lshl_add_u64 v[14:15], v[14:15], 1, s[0:1]
	s_waitcnt lgkmcnt(0)
; DI unsigned cvtpk(float lo, float hi) { f32x2 v = {lo, hi}; bf16x2_t b = __builtin_convertvector(v, bf16x2_t); return __builtin_bit_cast(unsigned, b); }
; DI float bflo(unsigned u) { return __uint_as_float(u << 16); }
; DI float bfhi(unsigned u) { return __uint_as_float(u & 0xffff0000u); }
; DI void d2_chunk(const Params& P, int l, int chunk, LAS float* Nm, LAS float* gs, int lane_in) {
;     ...
;     for (int t = 0; t < 2; ++t) { const float f = __expf(gs[32 * t + r]); const bf16_t* qrow = Qc + (32 * t + r) * 128 + 4 * hi;
; #pragma unroll
;         for (int G = 0; G < 8; ++G) { const u32x2 a = *(const u32x2*)(qrow + 16 * G), c2 = *(const u32x2*)(qrow + 16 * G + 8);
;             u32x4 o; o.x = cvtpk(bflo(a.x) * f, bfhi(a.x) * f); o.y = cvtpk(bflo(a.y) * f, bfhi(a.y) * f); o.z = cvtpk(bflo(c2.x) * f, bfhi(c2.x) * f); o.w = cvtpk(bflo(c2.y) * f, bfhi(c2.y) * f);
;             *(u32x4*)(QGf + ((t * 8 + G) * 64 + lane) * 8) = o; } }
	v_mul_f32_e32 v4, 0x3fb8aa3b, v1
	v_mul_f32_e32 v0, 0x3fb8aa3b, v0
	v_exp_f32_e32 v4, v4
	v_exp_f32_e32 v0, v0
	s_waitcnt vmcnt(30)
	v_lshlrev_b32_e32 v16, 16, v20
	v_and_b32_e32 v17, 0xffff0000, v20
	v_lshlrev_b32_e32 v18, 16, v21
	v_and_b32_e32 v19, 0xffff0000, v21
	v_pk_mul_f32 v[16:17], v[0:1], v[16:17] op_sel_hi:[0,1]
	v_pk_mul_f32 v[18:19], v[0:1], v[18:19] op_sel_hi:[0,1]
	v_cvt_pk_bf16_f32 v84, v16, v17
	v_cvt_pk_bf16_f32 v85, v18, v19
	v_lshlrev_b32_e32 v16, 16, v22
	v_and_b32_e32 v17, 0xffff0000, v22
	v_lshlrev_b32_e32 v18, 16, v23
	v_and_b32_e32 v19, 0xffff0000, v23
	v_pk_mul_f32 v[16:17], v[0:1], v[16:17] op_sel_hi:[0,1]
	v_pk_mul_f32 v[18:19], v[0:1], v[18:19] op_sel_hi:[0,1]
	v_cvt_pk_bf16_f32 v86, v16, v17
	v_cvt_pk_bf16_f32 v87, v18, v19
	global_store_dwordx4 v[8:9], v[84:87], off
	s_waitcnt vmcnt(29)
	v_lshlrev_b32_e32 v16, 16, v24
	v_and_b32_e32 v17, 0xffff0000, v24
	v_lshlrev_b32_e32 v18, 16, v25
	v_and_b32_e32 v19, 0xffff0000, v25
	v_pk_mul_f32 v[16:17], v[0:1], v[16:17] op_sel_hi:[0,1]
	v_pk_mul_f32 v[18:19], v[0:1], v[18:19] op_sel_hi:[0,1]
	v_cvt_pk_bf16_f32 v88, v16, v17
	v_cvt_pk_bf16_f32 v89, v18, v19
	v_lshlrev_b32_e32 v16, 16, v26
	v_and_b32_e32 v17, 0xffff0000, v26
	v_lshlrev_b32_e32 v18, 16, v27
	v_and_b32_e32 v19, 0xffff0000, v27
	v_pk_mul_f32 v[16:17], v[0:1], v[16:17] op_sel_hi:[0,1]
	v_pk_mul_f32 v[18:19], v[0:1], v[18:19] op_sel_hi:[0,1]
	v_cvt_pk_bf16_f32 v90, v16, v17
	v_cvt_pk_bf16_f32 v91, v18, v19
	global_store_dwordx4 v[8:9], v[88:91], off offset:1024
	s_waitcnt vmcnt(28)
	v_lshlrev_b32_e32 v16, 16, v28
	v_and_b32_e32 v17, 0xffff0000, v28
	v_lshlrev_b32_e32 v18, 16, v29
	v_and_b32_e32 v19, 0xffff0000, v29
	v_pk_mul_f32 v[16:17], v[0:1], v[16:17] op_sel_hi:[0,1]
	v_pk_mul_f32 v[18:19], v[0:1], v[18:19] op_sel_hi:[0,1]
	v_cvt_pk_bf16_f32 v84, v16, v17
	v_cvt_pk_bf16_f32 v85, v18, v19
	v_lshlrev_b32_e32 v16, 16, v30
	v_and_b32_e32 v17, 0xffff0000, v30
	v_lshlrev_b32_e32 v18, 16, v31
	v_and_b32_e32 v19, 0xffff0000, v31
	v_pk_mul_f32 v[16:17], v[0:1], v[16:17] op_sel_hi:[0,1]
	v_pk_mul_f32 v[18:19], v[0:1], v[18:19] op_sel_hi:[0,1]
	v_cvt_pk_bf16_f32 v86, v16, v17
	v_cvt_pk_bf16_f32 v87, v18, v19
	global_store_dwordx4 v[8:9], v[84:87], off offset:2048
	s_waitcnt vmcnt(27)
	v_lshlrev_b32_e32 v16, 16, v32
	v_and_b32_e32 v17, 0xffff0000, v32
	v_lshlrev_b32_e32 v18, 16, v33
	v_and_b32_e32 v19, 0xffff0000, v33
	v_pk_mul_f32 v[16:17], v[0:1], v[16:17] op_sel_hi:[0,1]
	v_pk_mul_f32 v[18:19], v[0:1], v[18:19] op_sel_hi:[0,1]
	v_cvt_pk_bf16_f32 v88, v16, v17
	v_cvt_pk_bf16_f32 v89, v18, v19
	v_lshlrev_b32_e32 v16, 16, v34
	v_and_b32_e32 v17, 0xffff0000, v34
	v_lshlrev_b32_e32 v18, 16, v35
	v_and_b32_e32 v19, 0xffff0000, v35
	v_pk_mul_f32 v[16:17], v[0:1], v[16:17] op_sel_hi:[0,1]
	v_pk_mul_f32 v[18:19], v[0:1], v[18:19] op_sel_hi:[0,1]
	v_cvt_pk_bf16_f32 v90, v16, v17
	v_cvt_pk_bf16_f32 v91, v18, v19
	global_store_dwordx4 v[8:9], v[88:91], off offset:3072
	s_waitcnt vmcnt(26)
	v_lshlrev_b32_e32 v16, 16, v36
	v_and_b32_e32 v17, 0xffff0000, v36
	v_lshlrev_b32_e32 v18, 16, v37
	v_and_b32_e32 v19, 0xffff0000, v37
	v_pk_mul_f32 v[16:17], v[0:1], v[16:17] op_sel_hi:[0,1]
	v_pk_mul_f32 v[18:19], v[0:1], v[18:19] op_sel_hi:[0,1]
	v_cvt_pk_bf16_f32 v84, v16, v17
	v_cvt_pk_bf16_f32 v85, v18, v19
	v_lshlrev_b32_e32 v16, 16, v38
	v_and_b32_e32 v17, 0xffff0000, v38
	v_lshlrev_b32_e32 v18, 16, v39
	v_and_b32_e32 v19, 0xffff0000, v39
	v_pk_mul_f32 v[16:17], v[0:1], v[16:17] op_sel_hi:[0,1]
	v_pk_mul_f32 v[18:19], v[0:1], v[18:19] op_sel_hi:[0,1]
	v_cvt_pk_bf16_f32 v86, v16, v17
	v_cvt_pk_bf16_f32 v87, v18, v19
	global_store_dwordx4 v[10:11], v[84:87], off
	s_waitcnt vmcnt(25)
	v_lshlrev_b32_e32 v16, 16, v40
	v_and_b32_e32 v17, 0xffff0000, v40
	v_lshlrev_b32_e32 v18, 16, v41
	v_and_b32_e32 v19, 0xffff0000, v41
	v_pk_mul_f32 v[16:17], v[0:1], v[16:17] op_sel_hi:[0,1]
	v_pk_mul_f32 v[18:19], v[0:1], v[18:19] op_sel_hi:[0,1]
	v_cvt_pk_bf16_f32 v88, v16, v17
	v_cvt_pk_bf16_f32 v89, v18, v19
	v_lshlrev_b32_e32 v16, 16, v42
	v_and_b32_e32 v17, 0xffff0000, v42
	v_lshlrev_b32_e32 v18, 16, v43
	v_and_b32_e32 v19, 0xffff0000, v43
	v_pk_mul_f32 v[16:17], v[0:1], v[16:17] op_sel_hi:[0,1]
	v_pk_mul_f32 v[18:19], v[0:1], v[18:19] op_sel_hi:[0,1]
	v_cvt_pk_bf16_f32 v90, v16, v17
	v_cvt_pk_bf16_f32 v91, v18, v19
	global_store_dwordx4 v[10:11], v[88:91], off offset:1024
	s_waitcnt vmcnt(24)
	v_lshlrev_b32_e32 v16, 16, v44
	v_and_b32_e32 v17, 0xffff0000, v44
	v_lshlrev_b32_e32 v18, 16, v45
	v_and_b32_e32 v19, 0xffff0000, v45
	v_pk_mul_f32 v[16:17], v[0:1], v[16:17] op_sel_hi:[0,1]
	v_pk_mul_f32 v[18:19], v[0:1], v[18:19] op_sel_hi:[0,1]
	v_cvt_pk_bf16_f32 v84, v16, v17
	v_cvt_pk_bf16_f32 v85, v18, v19
	v_lshlrev_b32_e32 v16, 16, v46
	v_and_b32_e32 v17, 0xffff0000, v46
	v_lshlrev_b32_e32 v18, 16, v47
	v_and_b32_e32 v19, 0xffff0000, v47
	v_pk_mul_f32 v[16:17], v[0:1], v[16:17] op_sel_hi:[0,1]
	v_pk_mul_f32 v[18:19], v[0:1], v[18:19] op_sel_hi:[0,1]
	v_cvt_pk_bf16_f32 v86, v16, v17
	v_cvt_pk_bf16_f32 v87, v18, v19
	global_store_dwordx4 v[10:11], v[84:87], off offset:2048
	s_waitcnt vmcnt(23)
	v_lshlrev_b32_e32 v16, 16, v48
	v_and_b32_e32 v17, 0xffff0000, v48
	v_lshlrev_b32_e32 v18, 16, v49
	v_and_b32_e32 v19, 0xffff0000, v49
	v_pk_mul_f32 v[16:17], v[0:1], v[16:17] op_sel_hi:[0,1]
	v_pk_mul_f32 v[18:19], v[0:1], v[18:19] op_sel_hi:[0,1]
	v_cvt_pk_bf16_f32 v88, v16, v17
	v_cvt_pk_bf16_f32 v89, v18, v19
	v_lshlrev_b32_e32 v16, 16, v50
	v_and_b32_e32 v17, 0xffff0000, v50
	v_lshlrev_b32_e32 v18, 16, v51
	v_and_b32_e32 v19, 0xffff0000, v51
	v_pk_mul_f32 v[16:17], v[0:1], v[16:17] op_sel_hi:[0,1]
	v_pk_mul_f32 v[18:19], v[0:1], v[18:19] op_sel_hi:[0,1]
	v_cvt_pk_bf16_f32 v90, v16, v17
	v_cvt_pk_bf16_f32 v91, v18, v19
	global_store_dwordx4 v[10:11], v[88:91], off offset:3072
	s_waitcnt vmcnt(22)
; DI unsigned cvtpk(float lo, float hi) { f32x2 v = {lo, hi}; bf16x2_t b = __builtin_convertvector(v, bf16x2_t); return __builtin_bit_cast(unsigned, b); }
; DI float bflo(unsigned u) { return __uint_as_float(u << 16); }
; DI float bfhi(unsigned u) { return __uint_as_float(u & 0xffff0000u); }
; DI void d2_chunk(const Params& P, int l, int chunk, LAS float* Nm, LAS float* gs, int lane_in) {
;     ...
;     for (int t = 0; t < 2; ++t) { const float f = __expf(gs[32 * t + r]); const bf16_t* qrow = Qc + (32 * t + r) * 128 + 4 * hi;
; #pragma unroll
;         for (int G = 0; G < 8; ++G) { const u32x2 a = *(const u32x2*)(qrow + 16 * G), c2 = *(const u32x2*)(qrow + 16 * G + 8);
;             u32x4 o; o.x = cvtpk(bflo(a.x) * f, bfhi(a.x) * f); o.y = cvtpk(bflo(a.y) * f, bfhi(a.y) * f); o.z = cvtpk(bflo(c2.x) * f, bfhi(c2.x) * f); o.w = cvtpk(bflo(c2.y) * f, bfhi(c2.y) * f);
;             *(u32x4*)(QGf + ((t * 8 + G) * 64 + lane) * 8) = o; } }
;     __builtin_amdgcn_sched_barrier(0); asm volatile("" ::: "memory");
;     if (lane == 0) ((float*)(P.ws + WS_GL))[chunk] = __expf(gcl);
	v_lshlrev_b32_e32 v16, 16, v52
	v_and_b32_e32 v17, 0xffff0000, v52
	v_lshlrev_b32_e32 v18, 16, v53
	v_and_b32_e32 v19, 0xffff0000, v53
	v_pk_mul_f32 v[16:17], v[4:5], v[16:17] op_sel_hi:[0,1]
	v_pk_mul_f32 v[18:19], v[4:5], v[18:19] op_sel_hi:[0,1]
	v_cvt_pk_bf16_f32 v84, v16, v17
	v_cvt_pk_bf16_f32 v85, v18, v19
	v_lshlrev_b32_e32 v16, 16, v54
	v_and_b32_e32 v17, 0xffff0000, v54
	v_lshlrev_b32_e32 v18, 16, v55
	v_and_b32_e32 v19, 0xffff0000, v55
	v_pk_mul_f32 v[16:17], v[4:5], v[16:17] op_sel_hi:[0,1]
	v_pk_mul_f32 v[18:19], v[4:5], v[18:19] op_sel_hi:[0,1]
	v_cvt_pk_bf16_f32 v86, v16, v17
	v_cvt_pk_bf16_f32 v87, v18, v19
	global_store_dwordx4 v[12:13], v[84:87], off
	s_waitcnt vmcnt(21)
	v_lshlrev_b32_e32 v16, 16, v56
	v_and_b32_e32 v17, 0xffff0000, v56
	v_lshlrev_b32_e32 v18, 16, v57
	v_and_b32_e32 v19, 0xffff0000, v57
	v_pk_mul_f32 v[16:17], v[4:5], v[16:17] op_sel_hi:[0,1]
	v_pk_mul_f32 v[18:19], v[4:5], v[18:19] op_sel_hi:[0,1]
	v_cvt_pk_bf16_f32 v88, v16, v17
	v_cvt_pk_bf16_f32 v89, v18, v19
	v_lshlrev_b32_e32 v16, 16, v58
	v_and_b32_e32 v17, 0xffff0000, v58
	v_lshlrev_b32_e32 v18, 16, v59
	v_and_b32_e32 v19, 0xffff0000, v59
	v_pk_mul_f32 v[16:17], v[4:5], v[16:17] op_sel_hi:[0,1]
	v_pk_mul_f32 v[18:19], v[4:5], v[18:19] op_sel_hi:[0,1]
	v_cvt_pk_bf16_f32 v90, v16, v17
	v_cvt_pk_bf16_f32 v91, v18, v19
	global_store_dwordx4 v[12:13], v[88:91], off offset:1024
	s_waitcnt vmcnt(20)
	v_lshlrev_b32_e32 v16, 16, v60
	v_and_b32_e32 v17, 0xffff0000, v60
	v_lshlrev_b32_e32 v18, 16, v61
	v_and_b32_e32 v19, 0xffff0000, v61
	v_pk_mul_f32 v[16:17], v[4:5], v[16:17] op_sel_hi:[0,1]
	v_pk_mul_f32 v[18:19], v[4:5], v[18:19] op_sel_hi:[0,1]
	v_cvt_pk_bf16_f32 v84, v16, v17
	v_cvt_pk_bf16_f32 v85, v18, v19
	v_lshlrev_b32_e32 v16, 16, v62
	v_and_b32_e32 v17, 0xffff0000, v62
	v_lshlrev_b32_e32 v18, 16, v63
	v_and_b32_e32 v19, 0xffff0000, v63
	v_pk_mul_f32 v[16:17], v[4:5], v[16:17] op_sel_hi:[0,1]
	v_pk_mul_f32 v[18:19], v[4:5], v[18:19] op_sel_hi:[0,1]
	v_cvt_pk_bf16_f32 v86, v16, v17
	v_cvt_pk_bf16_f32 v87, v18, v19
	global_store_dwordx4 v[12:13], v[84:87], off offset:2048
	s_waitcnt vmcnt(19)
	v_lshlrev_b32_e32 v16, 16, v64
	v_and_b32_e32 v17, 0xffff0000, v64
	v_lshlrev_b32_e32 v18, 16, v65
	v_and_b32_e32 v19, 0xffff0000, v65
	v_pk_mul_f32 v[16:17], v[4:5], v[16:17] op_sel_hi:[0,1]
	v_pk_mul_f32 v[18:19], v[4:5], v[18:19] op_sel_hi:[0,1]
	v_cvt_pk_bf16_f32 v88, v16, v17
	v_cvt_pk_bf16_f32 v89, v18, v19
	v_lshlrev_b32_e32 v16, 16, v66
	v_and_b32_e32 v17, 0xffff0000, v66
	v_lshlrev_b32_e32 v18, 16, v67
	v_and_b32_e32 v19, 0xffff0000, v67
	v_pk_mul_f32 v[16:17], v[4:5], v[16:17] op_sel_hi:[0,1]
	v_pk_mul_f32 v[18:19], v[4:5], v[18:19] op_sel_hi:[0,1]
	v_cvt_pk_bf16_f32 v90, v16, v17
	v_cvt_pk_bf16_f32 v91, v18, v19
	global_store_dwordx4 v[12:13], v[88:91], off offset:3072
	s_waitcnt vmcnt(18)
	v_lshlrev_b32_e32 v16, 16, v68
	v_and_b32_e32 v17, 0xffff0000, v68
	v_lshlrev_b32_e32 v18, 16, v69
	v_and_b32_e32 v19, 0xffff0000, v69
	v_pk_mul_f32 v[16:17], v[4:5], v[16:17] op_sel_hi:[0,1]
	v_pk_mul_f32 v[18:19], v[4:5], v[18:19] op_sel_hi:[0,1]
	v_cvt_pk_bf16_f32 v84, v16, v17
	v_cvt_pk_bf16_f32 v85, v18, v19
	v_lshlrev_b32_e32 v16, 16, v70
	v_and_b32_e32 v17, 0xffff0000, v70
	v_lshlrev_b32_e32 v18, 16, v71
	v_and_b32_e32 v19, 0xffff0000, v71
	v_pk_mul_f32 v[16:17], v[4:5], v[16:17] op_sel_hi:[0,1]
	v_pk_mul_f32 v[18:19], v[4:5], v[18:19] op_sel_hi:[0,1]
	v_cvt_pk_bf16_f32 v86, v16, v17
	v_cvt_pk_bf16_f32 v87, v18, v19
	global_store_dwordx4 v[14:15], v[84:87], off
	s_waitcnt vmcnt(17)
	v_lshlrev_b32_e32 v16, 16, v72
	v_and_b32_e32 v17, 0xffff0000, v72
	v_lshlrev_b32_e32 v18, 16, v73
	v_and_b32_e32 v19, 0xffff0000, v73
	v_pk_mul_f32 v[16:17], v[4:5], v[16:17] op_sel_hi:[0,1]
	v_pk_mul_f32 v[18:19], v[4:5], v[18:19] op_sel_hi:[0,1]
	v_cvt_pk_bf16_f32 v88, v16, v17
	v_cvt_pk_bf16_f32 v89, v18, v19
	v_lshlrev_b32_e32 v16, 16, v74
	v_and_b32_e32 v17, 0xffff0000, v74
	v_lshlrev_b32_e32 v18, 16, v75
	v_and_b32_e32 v19, 0xffff0000, v75
	v_pk_mul_f32 v[16:17], v[4:5], v[16:17] op_sel_hi:[0,1]
	v_pk_mul_f32 v[18:19], v[4:5], v[18:19] op_sel_hi:[0,1]
	v_cvt_pk_bf16_f32 v90, v16, v17
	v_cvt_pk_bf16_f32 v91, v18, v19
	global_store_dwordx4 v[14:15], v[88:91], off offset:1024
	s_waitcnt vmcnt(16)
	v_lshlrev_b32_e32 v16, 16, v76
	v_and_b32_e32 v17, 0xffff0000, v76
	v_lshlrev_b32_e32 v18, 16, v77
	v_and_b32_e32 v19, 0xffff0000, v77
	v_pk_mul_f32 v[16:17], v[4:5], v[16:17] op_sel_hi:[0,1]
	v_pk_mul_f32 v[18:19], v[4:5], v[18:19] op_sel_hi:[0,1]
	v_cvt_pk_bf16_f32 v84, v16, v17
	v_cvt_pk_bf16_f32 v85, v18, v19
	v_lshlrev_b32_e32 v16, 16, v78
	v_and_b32_e32 v17, 0xffff0000, v78
	v_lshlrev_b32_e32 v18, 16, v79
	v_and_b32_e32 v19, 0xffff0000, v79
	v_pk_mul_f32 v[16:17], v[4:5], v[16:17] op_sel_hi:[0,1]
	v_pk_mul_f32 v[18:19], v[4:5], v[18:19] op_sel_hi:[0,1]
	v_cvt_pk_bf16_f32 v86, v16, v17
	v_cvt_pk_bf16_f32 v87, v18, v19
	global_store_dwordx4 v[14:15], v[84:87], off offset:2048
	s_waitcnt vmcnt(15)
	v_lshlrev_b32_e32 v16, 16, v80
	v_and_b32_e32 v17, 0xffff0000, v80
	v_lshlrev_b32_e32 v18, 16, v81
	v_and_b32_e32 v19, 0xffff0000, v81
	v_pk_mul_f32 v[16:17], v[4:5], v[16:17] op_sel_hi:[0,1]
	v_pk_mul_f32 v[18:19], v[4:5], v[18:19] op_sel_hi:[0,1]
	v_cvt_pk_bf16_f32 v88, v16, v17
	v_cvt_pk_bf16_f32 v89, v18, v19
	v_lshlrev_b32_e32 v16, 16, v82
	v_and_b32_e32 v17, 0xffff0000, v82
	v_lshlrev_b32_e32 v18, 16, v83
	v_and_b32_e32 v19, 0xffff0000, v83
	v_pk_mul_f32 v[16:17], v[4:5], v[16:17] op_sel_hi:[0,1]
	v_pk_mul_f32 v[18:19], v[4:5], v[18:19] op_sel_hi:[0,1]
	v_cvt_pk_bf16_f32 v90, v16, v17
	v_cvt_pk_bf16_f32 v91, v18, v19
	global_store_dwordx4 v[14:15], v[88:91], off offset:3072
	s_and_saveexec_b64 s[0:1], vcc
	v_readlane_b32 s36, v255, 23
	v_readlane_b32 s37, v255, 24
	s_cbranch_execz .LBB0_380
	v_mul_f32_e32 v0, 0x3fb8aa3b, v191
	v_exp_f32_e32 v0, v0
	s_lshl_b64 s[4:5], s[36:37], 2
	v_readlane_b32 s8, v255, 21
	s_add_u32 s4, s8, s4
	v_readlane_b32 s8, v255, 22
	s_addc_u32 s5, s8, s5
	global_store_dword v97, v0, s[4:5]
	s_branch .LBB0_380
